# prologue adaLN GEMV k-loop: 32 weight-row loads in flight with one counted vmcnt ladder (was four drained batches of 8)
# baseline (speedup 1.0000x reference)
.LBB0_1588:
	s_mul_hi_u32 s19, s12, s8
	s_mul_i32 s18, s12, s8
	v_lshl_add_u64 v[224:225], s[18:19], 2, v[48:49]
	global_load_dword v112, v[224:225], off
	s_add_u32 s18, s18, s12
	s_addc_u32 s19, s19, 0
	v_lshl_add_u64 v[224:225], s[18:19], 2, v[48:49]
	global_load_dword v113, v[224:225], off
	s_add_u32 s18, s18, s12
	s_addc_u32 s19, s19, 0
	v_lshl_add_u64 v[224:225], s[18:19], 2, v[48:49]
	global_load_dword v114, v[224:225], off
	s_add_u32 s18, s18, s12
	s_addc_u32 s19, s19, 0
	v_lshl_add_u64 v[224:225], s[18:19], 2, v[48:49]
	global_load_dword v115, v[224:225], off
	s_add_u32 s18, s18, s12
	s_addc_u32 s19, s19, 0
	v_lshl_add_u64 v[224:225], s[18:19], 2, v[48:49]
	global_load_dword v116, v[224:225], off
	s_add_u32 s18, s18, s12
	s_addc_u32 s19, s19, 0
	v_lshl_add_u64 v[224:225], s[18:19], 2, v[48:49]
	global_load_dword v117, v[224:225], off
	s_add_u32 s18, s18, s12
	s_addc_u32 s19, s19, 0
	v_lshl_add_u64 v[224:225], s[18:19], 2, v[48:49]
	global_load_dword v118, v[224:225], off
	s_add_u32 s18, s18, s12
	s_addc_u32 s19, s19, 0
	v_lshl_add_u64 v[224:225], s[18:19], 2, v[48:49]
	global_load_dword v119, v[224:225], off
	s_add_u32 s18, s18, s12
	s_addc_u32 s19, s19, 0
	v_lshl_add_u64 v[224:225], s[18:19], 2, v[48:49]
	global_load_dword v120, v[224:225], off
	s_add_u32 s18, s18, s12
	s_addc_u32 s19, s19, 0
	v_lshl_add_u64 v[224:225], s[18:19], 2, v[48:49]
	global_load_dword v121, v[224:225], off
	s_add_u32 s18, s18, s12
	s_addc_u32 s19, s19, 0
	v_lshl_add_u64 v[224:225], s[18:19], 2, v[48:49]
	global_load_dword v122, v[224:225], off
	s_add_u32 s18, s18, s12
	s_addc_u32 s19, s19, 0
	v_lshl_add_u64 v[224:225], s[18:19], 2, v[48:49]
	global_load_dword v123, v[224:225], off
	s_add_u32 s18, s18, s12
	s_addc_u32 s19, s19, 0
	v_lshl_add_u64 v[224:225], s[18:19], 2, v[48:49]
	global_load_dword v124, v[224:225], off
	s_add_u32 s18, s18, s12
	s_addc_u32 s19, s19, 0
	v_lshl_add_u64 v[224:225], s[18:19], 2, v[48:49]
	global_load_dword v125, v[224:225], off
	s_add_u32 s18, s18, s12
	s_addc_u32 s19, s19, 0
	v_lshl_add_u64 v[224:225], s[18:19], 2, v[48:49]
	global_load_dword v126, v[224:225], off
	s_add_u32 s18, s18, s12
	s_addc_u32 s19, s19, 0
	v_lshl_add_u64 v[224:225], s[18:19], 2, v[48:49]
	global_load_dword v127, v[224:225], off
	s_add_u32 s18, s18, s12
	s_addc_u32 s19, s19, 0
	v_lshl_add_u64 v[224:225], s[18:19], 2, v[48:49]
	global_load_dword v128, v[224:225], off
	s_add_u32 s18, s18, s12
	s_addc_u32 s19, s19, 0
	v_lshl_add_u64 v[224:225], s[18:19], 2, v[48:49]
	global_load_dword v129, v[224:225], off
	s_add_u32 s18, s18, s12
	s_addc_u32 s19, s19, 0
	v_lshl_add_u64 v[224:225], s[18:19], 2, v[48:49]
	global_load_dword v130, v[224:225], off
	s_add_u32 s18, s18, s12
	s_addc_u32 s19, s19, 0
	v_lshl_add_u64 v[224:225], s[18:19], 2, v[48:49]
	global_load_dword v131, v[224:225], off
	s_add_u32 s18, s18, s12
	s_addc_u32 s19, s19, 0
	v_lshl_add_u64 v[224:225], s[18:19], 2, v[48:49]
	global_load_dword v132, v[224:225], off
	s_add_u32 s18, s18, s12
	s_addc_u32 s19, s19, 0
	v_lshl_add_u64 v[224:225], s[18:19], 2, v[48:49]
	global_load_dword v133, v[224:225], off
	s_add_u32 s18, s18, s12
	s_addc_u32 s19, s19, 0
	v_lshl_add_u64 v[224:225], s[18:19], 2, v[48:49]
	global_load_dword v134, v[224:225], off
	s_add_u32 s18, s18, s12
	s_addc_u32 s19, s19, 0
	v_lshl_add_u64 v[224:225], s[18:19], 2, v[48:49]
	global_load_dword v135, v[224:225], off
	s_add_u32 s18, s18, s12
	s_addc_u32 s19, s19, 0
	v_lshl_add_u64 v[224:225], s[18:19], 2, v[48:49]
	global_load_dword v136, v[224:225], off
	s_add_u32 s18, s18, s12
	s_addc_u32 s19, s19, 0
	v_lshl_add_u64 v[224:225], s[18:19], 2, v[48:49]
	global_load_dword v137, v[224:225], off
	s_add_u32 s18, s18, s12
	s_addc_u32 s19, s19, 0
	v_lshl_add_u64 v[224:225], s[18:19], 2, v[48:49]
	global_load_dword v138, v[224:225], off
	s_add_u32 s18, s18, s12
	s_addc_u32 s19, s19, 0
	v_lshl_add_u64 v[224:225], s[18:19], 2, v[48:49]
	global_load_dword v139, v[224:225], off
	s_add_u32 s18, s18, s12
	s_addc_u32 s19, s19, 0
	v_lshl_add_u64 v[224:225], s[18:19], 2, v[48:49]
	global_load_dword v140, v[224:225], off
	s_add_u32 s18, s18, s12
	s_addc_u32 s19, s19, 0
	v_lshl_add_u64 v[224:225], s[18:19], 2, v[48:49]
	global_load_dword v141, v[224:225], off
	s_add_u32 s18, s18, s12
	s_addc_u32 s19, s19, 0
	v_lshl_add_u64 v[224:225], s[18:19], 2, v[48:49]
	global_load_dword v142, v[224:225], off
	s_add_u32 s18, s18, s12
	s_addc_u32 s19, s19, 0
	v_lshl_add_u64 v[224:225], s[18:19], 2, v[48:49]
	global_load_dword v143, v[224:225], off
	s_lshl_b32 s9, s8, 2
	s_add_i32 s9, s15, s9
	v_mov_b32_e32 v226, s9
	ds_read_b128 v[192:195], v226
	ds_read_b128 v[196:199], v226 offset:16
	ds_read_b128 v[200:203], v226 offset:32
	ds_read_b128 v[204:207], v226 offset:48
	ds_read_b128 v[208:211], v226 offset:64
	ds_read_b128 v[212:215], v226 offset:80
	ds_read_b128 v[216:219], v226 offset:96
	ds_read_b128 v[220:223], v226 offset:112
	s_waitcnt lgkmcnt(0)
	s_waitcnt vmcnt(31)
	v_fmac_f32_e32 v26, v192, v112
	s_waitcnt vmcnt(30)
	v_fmac_f32_e32 v26, v193, v113
	s_waitcnt vmcnt(29)
	v_fmac_f32_e32 v26, v194, v114
	s_waitcnt vmcnt(28)
	v_fmac_f32_e32 v26, v195, v115
	s_waitcnt vmcnt(27)
	v_fmac_f32_e32 v26, v196, v116
	s_waitcnt vmcnt(26)
	v_fmac_f32_e32 v26, v197, v117
	s_waitcnt vmcnt(25)
	v_fmac_f32_e32 v26, v198, v118
	s_waitcnt vmcnt(24)
	v_fmac_f32_e32 v26, v199, v119
	s_waitcnt vmcnt(23)
	v_fmac_f32_e32 v26, v200, v120
	s_waitcnt vmcnt(22)
	v_fmac_f32_e32 v26, v201, v121
	s_waitcnt vmcnt(21)
	v_fmac_f32_e32 v26, v202, v122
	s_waitcnt vmcnt(20)
	v_fmac_f32_e32 v26, v203, v123
	s_waitcnt vmcnt(19)
	v_fmac_f32_e32 v26, v204, v124
	s_waitcnt vmcnt(18)
	v_fmac_f32_e32 v26, v205, v125
	s_waitcnt vmcnt(17)
	v_fmac_f32_e32 v26, v206, v126
	s_waitcnt vmcnt(16)
	v_fmac_f32_e32 v26, v207, v127
	s_waitcnt vmcnt(15)
	v_fmac_f32_e32 v26, v208, v128
	s_waitcnt vmcnt(14)
	v_fmac_f32_e32 v26, v209, v129
	s_waitcnt vmcnt(13)
	v_fmac_f32_e32 v26, v210, v130
	s_waitcnt vmcnt(12)
	v_fmac_f32_e32 v26, v211, v131
	s_waitcnt vmcnt(11)
	v_fmac_f32_e32 v26, v212, v132
	s_waitcnt vmcnt(10)
	v_fmac_f32_e32 v26, v213, v133
	s_waitcnt vmcnt(9)
	v_fmac_f32_e32 v26, v214, v134
	s_waitcnt vmcnt(8)
	v_fmac_f32_e32 v26, v215, v135
	s_waitcnt vmcnt(7)
	v_fmac_f32_e32 v26, v216, v136
	s_waitcnt vmcnt(6)
	v_fmac_f32_e32 v26, v217, v137
	s_waitcnt vmcnt(5)
	v_fmac_f32_e32 v26, v218, v138
	s_waitcnt vmcnt(4)
	v_fmac_f32_e32 v26, v219, v139
	s_waitcnt vmcnt(3)
	v_fmac_f32_e32 v26, v220, v140
	s_waitcnt vmcnt(2)
	v_fmac_f32_e32 v26, v221, v141
	s_waitcnt vmcnt(1)
	v_fmac_f32_e32 v26, v222, v142
	s_waitcnt vmcnt(0)
	v_fmac_f32_e32 v26, v223, v143
	ds_read_b128 v[192:195], v226 offset:4096
	ds_read_b128 v[196:199], v226 offset:4112
	ds_read_b128 v[200:203], v226 offset:4128
	ds_read_b128 v[204:207], v226 offset:4144
	ds_read_b128 v[208:211], v226 offset:4160
	ds_read_b128 v[212:215], v226 offset:4176
	ds_read_b128 v[216:219], v226 offset:4192
	ds_read_b128 v[220:223], v226 offset:4208
	s_waitcnt lgkmcnt(0)
	v_fmac_f32_e32 v27, v192, v112
	v_fmac_f32_e32 v27, v193, v113
	v_fmac_f32_e32 v27, v194, v114
	v_fmac_f32_e32 v27, v195, v115
	v_fmac_f32_e32 v27, v196, v116
	v_fmac_f32_e32 v27, v197, v117
	v_fmac_f32_e32 v27, v198, v118
	v_fmac_f32_e32 v27, v199, v119
	v_fmac_f32_e32 v27, v200, v120
	v_fmac_f32_e32 v27, v201, v121
	v_fmac_f32_e32 v27, v202, v122
	v_fmac_f32_e32 v27, v203, v123
	v_fmac_f32_e32 v27, v204, v124
	v_fmac_f32_e32 v27, v205, v125
	v_fmac_f32_e32 v27, v206, v126
	v_fmac_f32_e32 v27, v207, v127
	v_fmac_f32_e32 v27, v208, v128
	v_fmac_f32_e32 v27, v209, v129
	v_fmac_f32_e32 v27, v210, v130
	v_fmac_f32_e32 v27, v211, v131
	v_fmac_f32_e32 v27, v212, v132
	v_fmac_f32_e32 v27, v213, v133
	v_fmac_f32_e32 v27, v214, v134
	v_fmac_f32_e32 v27, v215, v135
	v_fmac_f32_e32 v27, v216, v136
	v_fmac_f32_e32 v27, v217, v137
	v_fmac_f32_e32 v27, v218, v138
	v_fmac_f32_e32 v27, v219, v139
	v_fmac_f32_e32 v27, v220, v140
	v_fmac_f32_e32 v27, v221, v141
	v_fmac_f32_e32 v27, v222, v142
	v_fmac_f32_e32 v27, v223, v143
	ds_read_b128 v[192:195], v226 offset:8192
	ds_read_b128 v[196:199], v226 offset:8208
	ds_read_b128 v[200:203], v226 offset:8224
	ds_read_b128 v[204:207], v226 offset:8240
	ds_read_b128 v[208:211], v226 offset:8256
	ds_read_b128 v[212:215], v226 offset:8272
	ds_read_b128 v[216:219], v226 offset:8288
	ds_read_b128 v[220:223], v226 offset:8304
	s_waitcnt lgkmcnt(0)
	v_fmac_f32_e32 v42, v192, v112
	v_fmac_f32_e32 v42, v193, v113
	v_fmac_f32_e32 v42, v194, v114
	v_fmac_f32_e32 v42, v195, v115
	v_fmac_f32_e32 v42, v196, v116
	v_fmac_f32_e32 v42, v197, v117
	v_fmac_f32_e32 v42, v198, v118
	v_fmac_f32_e32 v42, v199, v119
	v_fmac_f32_e32 v42, v200, v120
	v_fmac_f32_e32 v42, v201, v121
	v_fmac_f32_e32 v42, v202, v122
	v_fmac_f32_e32 v42, v203, v123
	v_fmac_f32_e32 v42, v204, v124
	v_fmac_f32_e32 v42, v205, v125
	v_fmac_f32_e32 v42, v206, v126
	v_fmac_f32_e32 v42, v207, v127
	v_fmac_f32_e32 v42, v208, v128
	v_fmac_f32_e32 v42, v209, v129
	v_fmac_f32_e32 v42, v210, v130
	v_fmac_f32_e32 v42, v211, v131
	v_fmac_f32_e32 v42, v212, v132
	v_fmac_f32_e32 v42, v213, v133
	v_fmac_f32_e32 v42, v214, v134
	v_fmac_f32_e32 v42, v215, v135
	v_fmac_f32_e32 v42, v216, v136
	v_fmac_f32_e32 v42, v217, v137
	v_fmac_f32_e32 v42, v218, v138
	v_fmac_f32_e32 v42, v219, v139
	v_fmac_f32_e32 v42, v220, v140
	v_fmac_f32_e32 v42, v221, v141
	v_fmac_f32_e32 v42, v222, v142
	v_fmac_f32_e32 v42, v223, v143
	ds_read_b128 v[192:195], v226 offset:12288
	ds_read_b128 v[196:199], v226 offset:12304
	ds_read_b128 v[200:203], v226 offset:12320
	ds_read_b128 v[204:207], v226 offset:12336
	ds_read_b128 v[208:211], v226 offset:12352
	ds_read_b128 v[212:215], v226 offset:12368
	ds_read_b128 v[216:219], v226 offset:12384
	ds_read_b128 v[220:223], v226 offset:12400
	s_waitcnt lgkmcnt(0)
	v_fmac_f32_e32 v43, v192, v112
	v_fmac_f32_e32 v43, v193, v113
	v_fmac_f32_e32 v43, v194, v114
	v_fmac_f32_e32 v43, v195, v115
	v_fmac_f32_e32 v43, v196, v116
	v_fmac_f32_e32 v43, v197, v117
	v_fmac_f32_e32 v43, v198, v118
	v_fmac_f32_e32 v43, v199, v119
	v_fmac_f32_e32 v43, v200, v120
	v_fmac_f32_e32 v43, v201, v121
	v_fmac_f32_e32 v43, v202, v122
	v_fmac_f32_e32 v43, v203, v123
	v_fmac_f32_e32 v43, v204, v124
	v_fmac_f32_e32 v43, v205, v125
	v_fmac_f32_e32 v43, v206, v126
	v_fmac_f32_e32 v43, v207, v127
	v_fmac_f32_e32 v43, v208, v128
	v_fmac_f32_e32 v43, v209, v129
	v_fmac_f32_e32 v43, v210, v130
	v_fmac_f32_e32 v43, v211, v131
	v_fmac_f32_e32 v43, v212, v132
	v_fmac_f32_e32 v43, v213, v133
	v_fmac_f32_e32 v43, v214, v134
	v_fmac_f32_e32 v43, v215, v135
	v_fmac_f32_e32 v43, v216, v136
	v_fmac_f32_e32 v43, v217, v137
	v_fmac_f32_e32 v43, v218, v138
	v_fmac_f32_e32 v43, v219, v139
	v_fmac_f32_e32 v43, v220, v140
	v_fmac_f32_e32 v43, v221, v141
	v_fmac_f32_e32 v43, v222, v142
	v_fmac_f32_e32 v43, v223, v143
	ds_read_b128 v[192:195], v226 offset:16384
	ds_read_b128 v[196:199], v226 offset:16400
	ds_read_b128 v[200:203], v226 offset:16416
	ds_read_b128 v[204:207], v226 offset:16432
	ds_read_b128 v[208:211], v226 offset:16448
	ds_read_b128 v[212:215], v226 offset:16464
	ds_read_b128 v[216:219], v226 offset:16480
	ds_read_b128 v[220:223], v226 offset:16496
	s_waitcnt lgkmcnt(0)
	v_fmac_f32_e32 v16, v192, v112
	v_fmac_f32_e32 v16, v193, v113
	v_fmac_f32_e32 v16, v194, v114
	v_fmac_f32_e32 v16, v195, v115
	v_fmac_f32_e32 v16, v196, v116
	v_fmac_f32_e32 v16, v197, v117
	v_fmac_f32_e32 v16, v198, v118
	v_fmac_f32_e32 v16, v199, v119
	v_fmac_f32_e32 v16, v200, v120
	v_fmac_f32_e32 v16, v201, v121
	v_fmac_f32_e32 v16, v202, v122
	v_fmac_f32_e32 v16, v203, v123
	v_fmac_f32_e32 v16, v204, v124
	v_fmac_f32_e32 v16, v205, v125
	v_fmac_f32_e32 v16, v206, v126
	v_fmac_f32_e32 v16, v207, v127
	v_fmac_f32_e32 v16, v208, v128
	v_fmac_f32_e32 v16, v209, v129
	v_fmac_f32_e32 v16, v210, v130
	v_fmac_f32_e32 v16, v211, v131
	v_fmac_f32_e32 v16, v212, v132
	v_fmac_f32_e32 v16, v213, v133
	v_fmac_f32_e32 v16, v214, v134
	v_fmac_f32_e32 v16, v215, v135
	v_fmac_f32_e32 v16, v216, v136
	v_fmac_f32_e32 v16, v217, v137
	v_fmac_f32_e32 v16, v218, v138
	v_fmac_f32_e32 v16, v219, v139
	v_fmac_f32_e32 v16, v220, v140
	v_fmac_f32_e32 v16, v221, v141
	v_fmac_f32_e32 v16, v222, v142
	v_fmac_f32_e32 v16, v223, v143
	ds_read_b128 v[192:195], v226 offset:20480
	ds_read_b128 v[196:199], v226 offset:20496
	ds_read_b128 v[200:203], v226 offset:20512
	ds_read_b128 v[204:207], v226 offset:20528
	ds_read_b128 v[208:211], v226 offset:20544
	ds_read_b128 v[212:215], v226 offset:20560
	ds_read_b128 v[216:219], v226 offset:20576
	ds_read_b128 v[220:223], v226 offset:20592
	s_waitcnt lgkmcnt(0)
	v_fmac_f32_e32 v17, v192, v112
	v_fmac_f32_e32 v17, v193, v113
	v_fmac_f32_e32 v17, v194, v114
	v_fmac_f32_e32 v17, v195, v115
	v_fmac_f32_e32 v17, v196, v116
	v_fmac_f32_e32 v17, v197, v117
	v_fmac_f32_e32 v17, v198, v118
	v_fmac_f32_e32 v17, v199, v119
	v_fmac_f32_e32 v17, v200, v120
	v_fmac_f32_e32 v17, v201, v121
	v_fmac_f32_e32 v17, v202, v122
	v_fmac_f32_e32 v17, v203, v123
	v_fmac_f32_e32 v17, v204, v124
	v_fmac_f32_e32 v17, v205, v125
	v_fmac_f32_e32 v17, v206, v126
	v_fmac_f32_e32 v17, v207, v127
	v_fmac_f32_e32 v17, v208, v128
	v_fmac_f32_e32 v17, v209, v129
	v_fmac_f32_e32 v17, v210, v130
	v_fmac_f32_e32 v17, v211, v131
	v_fmac_f32_e32 v17, v212, v132
	v_fmac_f32_e32 v17, v213, v133
	v_fmac_f32_e32 v17, v214, v134
	v_fmac_f32_e32 v17, v215, v135
	v_fmac_f32_e32 v17, v216, v136
	v_fmac_f32_e32 v17, v217, v137
	v_fmac_f32_e32 v17, v218, v138
	v_fmac_f32_e32 v17, v219, v139
	v_fmac_f32_e32 v17, v220, v140
	v_fmac_f32_e32 v17, v221, v141
	v_fmac_f32_e32 v17, v222, v142
	v_fmac_f32_e32 v17, v223, v143
	ds_read_b128 v[192:195], v226 offset:24576
	ds_read_b128 v[196:199], v226 offset:24592
	ds_read_b128 v[200:203], v226 offset:24608
	ds_read_b128 v[204:207], v226 offset:24624
	ds_read_b128 v[208:211], v226 offset:24640
	ds_read_b128 v[212:215], v226 offset:24656
	ds_read_b128 v[216:219], v226 offset:24672
	ds_read_b128 v[220:223], v226 offset:24688
	s_waitcnt lgkmcnt(0)
	v_fmac_f32_e32 v14, v192, v112
	v_fmac_f32_e32 v14, v193, v113
	v_fmac_f32_e32 v14, v194, v114
	v_fmac_f32_e32 v14, v195, v115
	v_fmac_f32_e32 v14, v196, v116
	v_fmac_f32_e32 v14, v197, v117
	v_fmac_f32_e32 v14, v198, v118
	v_fmac_f32_e32 v14, v199, v119
	v_fmac_f32_e32 v14, v200, v120
	v_fmac_f32_e32 v14, v201, v121
	v_fmac_f32_e32 v14, v202, v122
	v_fmac_f32_e32 v14, v203, v123
	v_fmac_f32_e32 v14, v204, v124
	v_fmac_f32_e32 v14, v205, v125
	v_fmac_f32_e32 v14, v206, v126
	v_fmac_f32_e32 v14, v207, v127
	v_fmac_f32_e32 v14, v208, v128
	v_fmac_f32_e32 v14, v209, v129
	v_fmac_f32_e32 v14, v210, v130
	v_fmac_f32_e32 v14, v211, v131
	v_fmac_f32_e32 v14, v212, v132
	v_fmac_f32_e32 v14, v213, v133
	v_fmac_f32_e32 v14, v214, v134
	v_fmac_f32_e32 v14, v215, v135
	v_fmac_f32_e32 v14, v216, v136
	v_fmac_f32_e32 v14, v217, v137
	v_fmac_f32_e32 v14, v218, v138
	v_fmac_f32_e32 v14, v219, v139
	v_fmac_f32_e32 v14, v220, v140
	v_fmac_f32_e32 v14, v221, v141
	v_fmac_f32_e32 v14, v222, v142
	v_fmac_f32_e32 v14, v223, v143
	ds_read_b128 v[192:195], v226 offset:28672
	ds_read_b128 v[196:199], v226 offset:28688
	ds_read_b128 v[200:203], v226 offset:28704
	ds_read_b128 v[204:207], v226 offset:28720
	ds_read_b128 v[208:211], v226 offset:28736
	ds_read_b128 v[212:215], v226 offset:28752
	ds_read_b128 v[216:219], v226 offset:28768
	ds_read_b128 v[220:223], v226 offset:28784
	s_waitcnt lgkmcnt(0)
	v_fmac_f32_e32 v15, v192, v112
	v_fmac_f32_e32 v15, v193, v113
	v_fmac_f32_e32 v15, v194, v114
	v_fmac_f32_e32 v15, v195, v115
	v_fmac_f32_e32 v15, v196, v116
	v_fmac_f32_e32 v15, v197, v117
	v_fmac_f32_e32 v15, v198, v118
	v_fmac_f32_e32 v15, v199, v119
	v_fmac_f32_e32 v15, v200, v120
	v_fmac_f32_e32 v15, v201, v121
	v_fmac_f32_e32 v15, v202, v122
	v_fmac_f32_e32 v15, v203, v123
	v_fmac_f32_e32 v15, v204, v124
	v_fmac_f32_e32 v15, v205, v125
	v_fmac_f32_e32 v15, v206, v126
	v_fmac_f32_e32 v15, v207, v127
	v_fmac_f32_e32 v15, v208, v128
	v_fmac_f32_e32 v15, v209, v129
	v_fmac_f32_e32 v15, v210, v130
	v_fmac_f32_e32 v15, v211, v131
	v_fmac_f32_e32 v15, v212, v132
	v_fmac_f32_e32 v15, v213, v133
	v_fmac_f32_e32 v15, v214, v134
	v_fmac_f32_e32 v15, v215, v135
	v_fmac_f32_e32 v15, v216, v136
	v_fmac_f32_e32 v15, v217, v137
	v_fmac_f32_e32 v15, v218, v138
	v_fmac_f32_e32 v15, v219, v139
	v_fmac_f32_e32 v15, v220, v140
	v_fmac_f32_e32 v15, v221, v141
	v_fmac_f32_e32 v15, v222, v142
	v_fmac_f32_e32 v15, v223, v143
	s_add_i32 s8, s8, 32
	s_cmpk_eq_i32 s8, 0x80
	s_cbranch_scc0 .LBB0_1588
	v_add_u32_e32 v2, s16, v47
	ds_write2st64_b32 v2, v26, v27 offset0:128 offset1:129
	ds_write2st64_b32 v2, v42, v43 offset0:130 offset1:131
	ds_write2st64_b32 v2, v16, v17 offset0:132 offset1:133
	ds_write2st64_b32 v2, v14, v15 offset0:134 offset1:135
	v_add_u32_e32 v2, s4, v46
	v_ashrrev_i32_e32 v3, 31, v2
	v_lshl_add_u64 v[2:3], v[2:3], 2, s[10:11]
	s_waitcnt lgkmcnt(0)
	s_barrier
	global_load_dword v12, v[2:3], off
	ds_read2st64_b32 v[4:5], v80 offset0:128 offset1:136
	ds_read2st64_b32 v[6:7], v80 offset0:144 offset1:152
	ds_read2st64_b32 v[8:9], v80 offset0:160 offset1:168
	ds_read2st64_b32 v[10:11], v80 offset0:176 offset1:184
	s_add_u32 s6, s46, s6
	s_waitcnt lgkmcnt(3)
	v_add_f32_e32 v4, 0, v4
	v_add_f32_e32 v4, v4, v5
	s_waitcnt lgkmcnt(2)
	v_add_f32_e32 v4, v4, v6
	v_add_f32_e32 v4, v4, v7
	s_waitcnt lgkmcnt(1)
	v_add_f32_e32 v4, v4, v8
	v_mad_i64_i32 v[2:3], s[8:9], s12, v146, 0
	s_addc_u32 s7, s47, s7
	v_add_f32_e32 v4, v4, v9
	v_lshl_add_u64 v[2:3], v[2:3], 2, s[6:7]
	s_waitcnt lgkmcnt(0)
	v_add_f32_e32 v4, v4, v10
	s_add_i32 s60, s60, s62
	v_lshl_add_u64 v[2:3], s[4:5], 2, v[2:3]
	v_add_f32_e32 v4, v4, v11
	s_cmpk_gt_i32 s60, 0x19f
	v_lshl_add_u64 v[2:3], v[2:3], 0, v[0:1]
	s_waitcnt vmcnt(0)
	v_add_f32_e32 v4, v4, v12
	global_store_dword v[2:3], v4, off
	s_barrier
	s_cbranch_scc0 .LBB0_1582
